# P0 RMSNorm row sum of squares reduced with DPP adds and v_permlane16/32_swap instead of six ds_bpermute round trips
# speedup vs baseline: 1.0079x; 1.0079x over previous
; __device__ __forceinline__ unsigned cvt_pk_bf16(float lo, float hi) { unsigned r; asm volatile("v_cvt_pk_bf16_f32 %0, %1, %2" : "=v"(r) : "v"(lo), "v"(hi)); return r; }
; __device__ __forceinline__ float wave_sum(float v) {
; #pragma unroll
;     for (int o = 1; o < 64; o <<= 1) v += __shfl_xor(v, o);
;     return v;
; }
; __device__ __forceinline__ void rmsnorm_row(const float* __restrict__ xrow, const float* __restrict__ g, bf16_t* __restrict__ orow, int lane) {
;     const f32x4* xr = (const f32x4*)xrow + lane; f32x4 v[8]; float s = 0.f;
; #pragma unroll
;     for (int j = 0; j < 8; ++j) { v[j] = xr[64 * j]; s += (v[j].x * v[j].x + v[j].y * v[j].y) + (v[j].z * v[j].z + v[j].w * v[j].w); }
;     const float r = 1.f / sqrtf(wave_sum(s) * (1.f / D_) + EPS_);
;     const f32x4* gr = (const f32x4*)g + lane; u32x2* o8 = (u32x2*)orow + lane;
; #pragma unroll
;     for (int j = 0; j < 8; ++j) { const f32x4 gg = gr[64 * j]; u32x2 o; o.x = cvt_pk_bf16(v[j].x * r * gg.x, v[j].y * r * gg.y); o.y = cvt_pk_bf16(v[j].z * r * gg.z, v[j].w * r * gg.w); o8[64 * j] = o; }
; }
.LBB0_188:
	v_add_co_u32_e32 v62, vcc, 0xfffff000, v24
	global_load_dwordx4 v[34:37], v[24:25], off offset:-3072
	global_load_dwordx4 v[38:41], v[24:25], off offset:-2048
	global_load_dwordx4 v[42:45], v[24:25], off offset:-1024
	global_load_dwordx4 v[6:9], v[24:25], off
	v_addc_co_u32_e32 v63, vcc, -1, v25, vcc
	global_load_dwordx4 v[46:49], v[62:63], off offset:-3072
	global_load_dwordx4 v[50:53], v[62:63], off offset:-2048
	global_load_dwordx4 v[54:57], v[62:63], off offset:-1024
	global_load_dwordx4 v[58:61], v[24:25], off offset:-4096
	s_add_i32 s10, s10, s82
	s_cmpk_gt_i32 s10, 0x3fff
	v_lshl_add_u64 v[24:25], v[24:25], 0, s[8:9]
	s_waitcnt vmcnt(7)
	v_mul_f32_e32 v33, v35, v35
	v_mul_f32_e32 v62, v37, v37
	s_waitcnt vmcnt(6)
	v_mul_f32_e32 v63, v39, v39
	v_mul_f32_e32 v64, v41, v41
	s_waitcnt vmcnt(5)
	v_mul_f32_e32 v65, v43, v43
	v_mul_f32_e32 v66, v45, v45
	s_waitcnt vmcnt(3)
	v_mul_f32_e32 v69, v47, v47
	v_mul_f32_e32 v70, v49, v49
	s_waitcnt vmcnt(2)
	v_mul_f32_e32 v71, v51, v51
	v_mul_f32_e32 v72, v53, v53
	v_mul_f32_e32 v67, v7, v7
	v_mul_f32_e32 v68, v9, v9
	v_fmac_f32_e32 v33, v34, v34
	v_fmac_f32_e32 v62, v36, v36
	v_fmac_f32_e32 v63, v38, v38
	v_fmac_f32_e32 v64, v40, v40
	v_fmac_f32_e32 v65, v42, v42
	v_fmac_f32_e32 v66, v44, v44
	s_waitcnt vmcnt(1)
	v_mul_f32_e32 v73, v55, v55
	v_mul_f32_e32 v74, v57, v57
	v_fmac_f32_e32 v69, v46, v46
	v_fmac_f32_e32 v70, v48, v48
	v_fmac_f32_e32 v71, v50, v50
	v_fmac_f32_e32 v72, v52, v52
	v_fmac_f32_e32 v67, v6, v6
	v_fmac_f32_e32 v68, v8, v8
	s_waitcnt vmcnt(0)
	v_mul_f32_e32 v75, v59, v59
	v_mul_f32_e32 v76, v61, v61
	v_add_f32_e32 v33, v33, v62
	v_add_f32_e32 v62, v63, v64
	v_add_f32_e32 v63, v65, v66
	v_fmac_f32_e32 v73, v54, v54
	v_fmac_f32_e32 v74, v56, v56
	v_add_f32_e32 v65, v69, v70
	v_add_f32_e32 v66, v71, v72
	v_add_f32_e32 v64, v67, v68
	v_fmac_f32_e32 v75, v58, v58
	v_fmac_f32_e32 v76, v60, v60
	v_add_f32_e32 v67, v73, v74
	v_add_f32_e32 v65, v65, v66
	v_add_f32_e32 v68, v75, v76
	v_add_f32_e32 v65, v65, v67
	v_add_f32_e32 v65, v65, v68
	v_add_f32_e32 v33, v65, v33
	v_add_f32_e32 v33, v33, v62
	v_add_f32_e32 v33, v33, v63
	v_add_f32_e32 v33, v33, v64
	s_nop 1
	v_add_f32_dpp v33, v33, v33 quad_perm:[1,0,3,2] row_mask:0xf bank_mask:0xf
	s_nop 1
	v_add_f32_dpp v33, v33, v33 quad_perm:[2,3,0,1] row_mask:0xf bank_mask:0xf
	s_nop 1
	v_add_f32_dpp v33, v33, v33 row_half_mirror row_mask:0xf bank_mask:0xf
	s_nop 1
	v_add_f32_dpp v33, v33, v33 row_ror:8 row_mask:0xf bank_mask:0xf
	v_mov_b32_e32 v62, v33
	s_nop 1
	v_permlane16_swap_b32_e32 v33, v62
	v_add_f32_e32 v33, v33, v62
	v_mov_b32_e32 v62, v33
	s_nop 1
	v_permlane32_swap_b32_e32 v33, v62
	v_add_f32_e32 v33, v33, v62
	v_fmamk_f32 v33, v33, 0x3a000000, v11
	v_mul_f32_e32 v62, 0x4f800000, v33
	v_cmp_gt_f32_e32 vcc, s3, v33
	s_nop 1
	v_cndmask_b32_e32 v33, v33, v62, vcc
	v_sqrt_f32_e32 v62, v33
	s_nop 0
	v_add_u32_e32 v63, -1, v62
	v_add_u32_e32 v64, 1, v62
	v_fma_f32 v65, -v63, v62, v33
	v_fma_f32 v66, -v64, v62, v33
	v_cmp_ge_f32_e64 s[0:1], 0, v65
	s_nop 1
	v_cndmask_b32_e64 v62, v62, v63, s[0:1]
	v_cmp_lt_f32_e64 s[0:1], 0, v66
	s_nop 1
	v_cndmask_b32_e64 v62, v62, v64, s[0:1]
	v_mul_f32_e32 v63, 0x37800000, v62
	v_cndmask_b32_e32 v62, v62, v63, vcc
	v_cmp_class_f32_e32 vcc, v33, v32
	s_nop 1
	v_cndmask_b32_e32 v33, v62, v33, vcc
	v_div_scale_f32 v62, s[0:1], v33, v33, 1.0
	v_rcp_f32_e32 v64, v62
	v_div_scale_f32 v63, vcc, 1.0, v33, 1.0
	v_fma_f32 v65, -v62, v64, 1.0
	v_fmac_f32_e32 v64, v65, v64
	v_mul_f32_e32 v65, v63, v64
	v_fma_f32 v66, -v62, v65, v63
	v_fmac_f32_e32 v65, v66, v64
	v_fma_f32 v62, -v62, v65, v63
	v_div_fmas_f32 v62, v62, v64, v65
	v_div_fixup_f32 v33, v62, v33, 1.0
	v_mul_f32_e32 v46, v46, v33
	v_mul_f32_e32 v47, v47, v33
	v_mul_f32_e32 v48, v48, v33
	v_mul_f32_e32 v49, v49, v33
	v_mul_f32_e32 v46, v2, v46
	v_mul_f32_e32 v47, v3, v47
	v_mul_f32_e32 v48, v4, v48
	v_mul_f32_e32 v49, v5, v49
	v_cvt_pk_bf16_f32 v62, v46, v47
	v_cvt_pk_bf16_f32 v63, v48, v49
	v_mul_f32_e32 v50, v50, v33
	v_mul_f32_e32 v51, v51, v33
	v_mul_f32_e32 v52, v52, v33
	v_mul_f32_e32 v53, v53, v33
	global_store_dwordx2 v[22:23], v[62:63], off offset:-3584
	v_mul_f32_e32 v34, v34, v33
	v_mul_f32_e32 v35, v35, v33
	v_mul_f32_e32 v36, v36, v33
	v_mul_f32_e32 v37, v37, v33
	v_mul_f32_e32 v38, v38, v33
	v_mul_f32_e32 v39, v39, v33
	v_mul_f32_e32 v40, v40, v33
	v_mul_f32_e32 v41, v41, v33
	v_mul_f32_e32 v6, v6, v33
	v_mul_f32_e32 v7, v7, v33
	v_mul_f32_e32 v8, v8, v33
	v_mul_f32_e32 v9, v9, v33
	v_mul_f32_e32 v46, v152, v50
	v_mul_f32_e32 v47, v153, v51
	v_mul_f32_e32 v48, v154, v52
	v_mul_f32_e32 v49, v155, v53
	v_cvt_pk_bf16_f32 v50, v46, v47
	v_cvt_pk_bf16_f32 v51, v48, v49
	v_mul_f32_e32 v52, v54, v33
	v_mul_f32_e32 v53, v55, v33
	v_mul_f32_e32 v54, v56, v33
	v_mul_f32_e32 v55, v57, v33
	global_store_dwordx2 v[22:23], v[50:51], off offset:-3072
	v_mul_f32_e32 v46, v52, v156
	v_mul_f32_e32 v47, v53, v157
	v_mul_f32_e32 v48, v54, v158
	v_mul_f32_e32 v49, v55, v159
	v_cvt_pk_bf16_f32 v50, v46, v47
	v_cvt_pk_bf16_f32 v51, v48, v49
	v_mul_f32_e32 v52, v58, v33
	v_mul_f32_e32 v53, v59, v33
	v_mul_f32_e32 v54, v60, v33
	v_mul_f32_e32 v55, v61, v33
	global_store_dwordx2 v[22:23], v[50:51], off offset:-2560
	v_mul_f32_e32 v46, v52, v160
	v_mul_f32_e32 v47, v53, v161
	v_mul_f32_e32 v48, v54, v162
	v_mul_f32_e32 v49, v55, v163
	v_cvt_pk_bf16_f32 v50, v46, v47
	v_cvt_pk_bf16_f32 v51, v48, v49
	v_mul_f32_e32 v34, v34, v164
	v_mul_f32_e32 v35, v35, v165
	v_mul_f32_e32 v36, v36, v166
	v_mul_f32_e32 v37, v37, v167
	global_store_dwordx2 v[22:23], v[50:51], off offset:-2048
	v_cvt_pk_bf16_f32 v46, v34, v35
	v_cvt_pk_bf16_f32 v47, v36, v37
	v_mul_f32_e32 v34, v38, v168
	v_mul_f32_e32 v35, v39, v169
	v_mul_f32_e32 v36, v40, v170
	v_mul_f32_e32 v37, v41, v171
	global_store_dwordx2 v[22:23], v[46:47], off offset:-1536
	v_cvt_pk_bf16_f32 v38, v34, v35
	v_cvt_pk_bf16_f32 v39, v36, v37
	v_mul_f32_e32 v40, v42, v33
	v_mul_f32_e32 v41, v43, v33
	v_mul_f32_e32 v42, v44, v33
	v_mul_f32_e32 v43, v45, v33
	global_store_dwordx2 v[22:23], v[38:39], off offset:-1024
	v_mul_f32_e32 v34, v40, v172
	v_mul_f32_e32 v35, v41, v173
	v_mul_f32_e32 v36, v42, v174
	v_mul_f32_e32 v37, v43, v175
	v_cvt_pk_bf16_f32 v38, v34, v35
	v_cvt_pk_bf16_f32 v39, v36, v37
	v_mul_f32_e32 v6, v6, v176
	v_mul_f32_e32 v7, v7, v177
	global_store_dwordx2 v[22:23], v[38:39], off offset:-512
	v_mul_f32_e32 v8, v8, v178
	v_mul_f32_e32 v9, v9, v179
	v_cvt_pk_bf16_f32 v6, v6, v7
	v_cvt_pk_bf16_f32 v7, v8, v9
	global_store_dwordx2 v[22:23], v[6:7], off
	v_lshl_add_u64 v[22:23], v[22:23], 0, s[6:7]
	s_cbranch_scc0 .LBB0_188
	s_nop 0
